# baseline (speedup 1.0000x reference)
; #define LAS __attribute__((address_space(3)))
; __device__ __forceinline__ unsigned cvt_pk_bf16(float lo, float hi) { const f32x2 v = {lo, hi}; const bf16v2 r = __builtin_convertvector(v, bf16v2); return __builtin_bit_cast(unsigned, r); }
; __device__ __forceinline__ void convert_tile(LAS float* tile, const float* __restrict__ src, int N, int k0, int n0, bf16_t* __restrict__ dst, int K, int dst_row0) {
;     ...
;     for (int i = 0; i < 2; ++i) { const int idx = tid + 512 * i, k = idx >> 4, n4 = (idx & 15) * 4;
;         const f32x4 v = *(const f32x4*)(src + (size_t)(k0 + k) * N + n0 + n4);
;         tile[k * 65 + n4] = v[0]; tile[k * 65 + n4 + 1] = v[1]; tile[k * 65 + n4 + 2] = v[2]; tile[k * 65 + n4 + 3] = v[3]; }
;     __syncthreads();
;     { const int n = tid >> 3, kc = (tid & 7) * 8; float f[8];
; #pragma unroll
;       for (int j = 0; j < 8; ++j) f[j] = tile[(kc + j) * 65 + n];
;       u32x4 w; w.x = cvt_pk_bf16(f[0], f[1]); w.y = cvt_pk_bf16(f[2], f[3]); w.z = cvt_pk_bf16(f[4], f[5]); w.w = cvt_pk_bf16(f[6], f[7]);
;       *(u32x4*)(dst + (size_t)(dst_row0 + n) * K + k0 + kc) = w; }
;     __syncthreads();
; }
; __device__ void convert_mat(LAS float* tile, const float* src, int K, int N, bf16_t* dst, int mode, int rank, int stride) {
;     const int nnt = N / 64, nt = (K / 64) * nnt;
;     for (int t = rank; t < nt; t += stride) { const int kt = t / nnt, n0 = (t % nnt) * 64;
;         const int drow = mode == 0 ? n0 : (n0 >> 7) * 256 + (n0 & 127) + (mode - 1) * 128;
;         convert_tile(tile, src, N, kt * 64, n0, dst, K, drow); }
.LBB0_379:
	s_mul_hi_i32 s0, s2, 0x2fa0be83
	s_lshr_b32 s1, s0, 31
	s_ashr_i32 s0, s0, 4
	s_add_i32 s0, s0, s1
	s_mul_i32 s1, s0, 0xffffea80
	s_add_i32 s14, s5, s1
	s_mul_i32 s1, s0, 0xffffd500
	s_add_i32 s1, s7, s1
	s_and_b32 s1, s1, 0xffffff00
	s_and_b32 s13, s14, 64
	s_ashr_i32 s15, s14, 31
	s_or_b32 s1, s13, s1
	s_lshl_b32 s0, s0, 6
	v_mov_b32_e32 v10, v226
	s_lshl_b64 s[14:15], s[14:15], 2
	s_add_u32 s14, s3, s14
	v_lshlrev_b32_e32 v0, 4, v10
	s_addc_u32 s15, s4, s15
	v_and_b32_e32 v0, 0xf0, v0
	v_ashrrev_i32_e32 v8, 4, v10
	v_lshl_add_u64 v[6:7], s[14:15], 0, v[0:1]
	v_add_u32_e32 v2, s0, v8
	v_mad_i64_i32 v[2:3], s[14:15], v2, s16, v[6:7]
	global_load_dwordx4 v[2:5], v[2:3], off
	v_add_u32_e32 v0, 0, v0
	v_mad_u64_u32 v[8:9], s[14:15], v8, s17, v[0:1]
	s_add_i32 s2, s2, s10
	s_add_i32 s5, s5, s6
	s_add_i32 s7, s7, s12
	v_add_u32_e32 v92, 0x200, v10
	v_ashrrev_i32_e32 v96, 4, v92
	v_add_u32_e32 v92, s0, v96
	v_mad_i64_i32 v[92:93], s[14:15], v92, s16, v[6:7]
	global_load_dwordx4 v[92:95], v[92:93], off
	v_mad_u64_u32 v[6:7], s[14:15], v96, s17, v[0:1]
	s_waitcnt vmcnt(1)
	ds_write2_b32 v8, v2, v3 offset1:1
	ds_write2_b32 v8, v4, v5 offset0:2 offset1:3
	v_ashrrev_i32_e32 v0, 3, v10
	s_waitcnt vmcnt(0)
	ds_write2_b32 v6, v92, v93 offset1:1
	ds_write2_b32 v6, v94, v95 offset0:2 offset1:3
	v_lshlrev_b32_e32 v2, 3, v10
	v_and_b32_e32 v10, 56, v2
	v_lshlrev_b32_e32 v2, 2, v0
	v_mul_u32_u24_e32 v3, 0x104, v10
	v_add3_u32 v6, 0, v2, v3
	s_waitcnt lgkmcnt(0)
	s_barrier
	ds_read2_b32 v[2:3], v6 offset1:65
	ds_read2_b32 v[4:5], v6 offset0:130 offset1:195
	v_add_u32_e32 v8, 0x400, v6
	ds_read2_b32 v[6:7], v8 offset0:4 offset1:69
	ds_read2_b32 v[8:9], v8 offset0:134 offset1:199
	s_waitcnt lgkmcnt(3)
	v_cvt_pk_bf16_f32 v2, v2, v3
	s_waitcnt lgkmcnt(2)
	v_cvt_pk_bf16_f32 v3, v4, v5
	s_waitcnt lgkmcnt(1)
	v_cvt_pk_bf16_f32 v4, v6, v7
	v_add_u32_e32 v6, s1, v0
	v_ashrrev_i32_e32 v7, 31, v6
	v_lshlrev_b64 v[6:7], 12, v[6:7]
	v_lshl_add_u64 v[6:7], s[98:99], 0, v[6:7]
	s_ashr_i32 s1, s0, 31
	v_lshl_add_u64 v[6:7], s[0:1], 1, v[6:7]
	v_lshlrev_b32_e32 v0, 1, v10
	s_waitcnt lgkmcnt(0)
	v_cvt_pk_bf16_f32 v5, v8, v9
	v_lshl_add_u64 v[6:7], v[6:7], 0, v[0:1]
	s_cmpk_lt_i32 s2, 0xac0
	global_store_dwordx4 v[6:7], v[2:5], off
	s_barrier
	s_cbranch_scc1 .LBB0_379

; #define LAS __attribute__((address_space(3)))
; __device__ __forceinline__ unsigned cvt_pk_bf16(float lo, float hi) { const f32x2 v = {lo, hi}; const bf16v2 r = __builtin_convertvector(v, bf16v2); return __builtin_bit_cast(unsigned, r); }
; __device__ __forceinline__ void convert_tile(LAS float* tile, const float* __restrict__ src, int N, int k0, int n0, bf16_t* __restrict__ dst, int K, int dst_row0) {
;     ...
;     for (int i = 0; i < 2; ++i) { const int idx = tid + 512 * i, k = idx >> 4, n4 = (idx & 15) * 4;
;         const f32x4 v = *(const f32x4*)(src + (size_t)(k0 + k) * N + n0 + n4);
;         tile[k * 65 + n4] = v[0]; tile[k * 65 + n4 + 1] = v[1]; tile[k * 65 + n4 + 2] = v[2]; tile[k * 65 + n4 + 3] = v[3]; }
;     __syncthreads();
;     { const int n = tid >> 3, kc = (tid & 7) * 8; float f[8];
; #pragma unroll
;       for (int j = 0; j < 8; ++j) f[j] = tile[(kc + j) * 65 + n];
;       u32x4 w; w.x = cvt_pk_bf16(f[0], f[1]); w.y = cvt_pk_bf16(f[2], f[3]); w.z = cvt_pk_bf16(f[4], f[5]); w.w = cvt_pk_bf16(f[6], f[7]);
;       *(u32x4*)(dst + (size_t)(dst_row0 + n) * K + k0 + kc) = w; }
;     __syncthreads();
; }
; __device__ void convert_mat(LAS float* tile, const float* src, int K, int N, bf16_t* dst, int mode, int rank, int stride) {
;     const int nnt = N / 64, nt = (K / 64) * nnt;
;     for (int t = rank; t < nt; t += stride) { const int kt = t / nnt, n0 = (t % nnt) * 64;
;         const int drow = mode == 0 ? n0 : (n0 >> 7) * 256 + (n0 & 127) + (mode - 1) * 128;
;         convert_tile(tile, src, N, kt * 64, n0, dst, K, drow); }
.LBB0_382:
	s_mul_hi_i32 s0, s2, 0x2fa0be83
	s_lshr_b32 s1, s0, 31
	s_ashr_i32 s0, s0, 4
	s_add_i32 s0, s0, s1
	s_mul_i32 s1, s0, 0xffffea80
	s_add_i32 s14, s5, s1
	s_and_b32 s1, s5, 64
	s_mul_i32 s13, s0, 0x2b00
	s_sub_i32 s1, s1, s13
	s_add_i32 s1, s7, s1
	s_ashr_i32 s15, s14, 31
	s_bitset1_b32 s1, 7
	s_lshl_b32 s0, s0, 6
	v_mov_b32_e32 v10, v226
	s_lshl_b64 s[14:15], s[14:15], 2
	s_add_u32 s14, s3, s14
	v_lshlrev_b32_e32 v0, 4, v10
	s_addc_u32 s15, s4, s15
	v_and_b32_e32 v0, 0xf0, v0
	v_ashrrev_i32_e32 v8, 4, v10
	v_lshl_add_u64 v[6:7], s[14:15], 0, v[0:1]
	v_add_u32_e32 v2, s0, v8
	v_mad_i64_i32 v[2:3], s[14:15], v2, s16, v[6:7]
	global_load_dwordx4 v[2:5], v[2:3], off
	v_add_u32_e32 v0, 0, v0
	v_mad_u64_u32 v[8:9], s[14:15], v8, s17, v[0:1]
	s_add_i32 s2, s2, s10
	s_add_i32 s5, s5, s6
	s_add_i32 s7, s7, s12
	v_add_u32_e32 v92, 0x200, v10
	v_ashrrev_i32_e32 v96, 4, v92
	v_add_u32_e32 v92, s0, v96
	v_mad_i64_i32 v[92:93], s[14:15], v92, s16, v[6:7]
	global_load_dwordx4 v[92:95], v[92:93], off
	v_mad_u64_u32 v[6:7], s[14:15], v96, s17, v[0:1]
	s_waitcnt vmcnt(1)
	ds_write2_b32 v8, v2, v3 offset1:1
	ds_write2_b32 v8, v4, v5 offset0:2 offset1:3
	v_ashrrev_i32_e32 v0, 3, v10
	s_waitcnt vmcnt(0)
	ds_write2_b32 v6, v92, v93 offset1:1
	ds_write2_b32 v6, v94, v95 offset0:2 offset1:3
	v_lshlrev_b32_e32 v2, 3, v10
	v_and_b32_e32 v10, 56, v2
	v_lshlrev_b32_e32 v2, 2, v0
	v_mul_u32_u24_e32 v3, 0x104, v10
	v_add3_u32 v6, 0, v2, v3
	s_waitcnt lgkmcnt(0)
	s_barrier
	ds_read2_b32 v[2:3], v6 offset1:65
	ds_read2_b32 v[4:5], v6 offset0:130 offset1:195
	v_add_u32_e32 v8, 0x400, v6
	ds_read2_b32 v[6:7], v8 offset0:4 offset1:69
	ds_read2_b32 v[8:9], v8 offset0:134 offset1:199
	s_waitcnt lgkmcnt(3)
	v_cvt_pk_bf16_f32 v2, v2, v3
	s_waitcnt lgkmcnt(2)
	v_cvt_pk_bf16_f32 v3, v4, v5
	s_waitcnt lgkmcnt(1)
	v_cvt_pk_bf16_f32 v4, v6, v7
	v_add_u32_e32 v6, s1, v0
	v_ashrrev_i32_e32 v7, 31, v6
	v_lshlrev_b64 v[6:7], 12, v[6:7]
	v_lshl_add_u64 v[6:7], s[98:99], 0, v[6:7]
	s_ashr_i32 s1, s0, 31
	v_lshl_add_u64 v[6:7], s[0:1], 1, v[6:7]
	v_lshlrev_b32_e32 v0, 1, v10
	s_waitcnt lgkmcnt(0)
	v_cvt_pk_bf16_f32 v5, v8, v9
	v_lshl_add_u64 v[6:7], v[6:7], 0, v[0:1]
	s_cmpk_gt_i32 s2, 0xabf
	global_store_dwordx4 v[6:7], v[2:5], off
	s_barrier
	s_cbranch_scc0 .LBB0_382

; #define LAS __attribute__((address_space(3)))
; __device__ __forceinline__ unsigned cvt_pk_bf16(float lo, float hi) { const f32x2 v = {lo, hi}; const bf16v2 r = __builtin_convertvector(v, bf16v2); return __builtin_bit_cast(unsigned, r); }
; __device__ __forceinline__ void convert_tile(LAS float* tile, const float* __restrict__ src, int N, int k0, int n0, bf16_t* __restrict__ dst, int K, int dst_row0) {
;     ...
;     for (int i = 0; i < 2; ++i) { const int idx = tid + 512 * i, k = idx >> 4, n4 = (idx & 15) * 4;
;         const f32x4 v = *(const f32x4*)(src + (size_t)(k0 + k) * N + n0 + n4);
;         tile[k * 65 + n4] = v[0]; tile[k * 65 + n4 + 1] = v[1]; tile[k * 65 + n4 + 2] = v[2]; tile[k * 65 + n4 + 3] = v[3]; }
;     __syncthreads();
;     { const int n = tid >> 3, kc = (tid & 7) * 8; float f[8];
; #pragma unroll
;       for (int j = 0; j < 8; ++j) f[j] = tile[(kc + j) * 65 + n];
;       u32x4 w; w.x = cvt_pk_bf16(f[0], f[1]); w.y = cvt_pk_bf16(f[2], f[3]); w.z = cvt_pk_bf16(f[4], f[5]); w.w = cvt_pk_bf16(f[6], f[7]);
;       *(u32x4*)(dst + (size_t)(dst_row0 + n) * K + k0 + kc) = w; }
;     __syncthreads();
; }
; __device__ void convert_mat(LAS float* tile, const float* src, int K, int N, bf16_t* dst, int mode, int rank, int stride) {
;     const int nnt = N / 64, nt = (K / 64) * nnt;
;     for (int t = rank; t < nt; t += stride) { const int kt = t / nnt, n0 = (t % nnt) * 64;
;         const int drow = mode == 0 ? n0 : (n0 >> 7) * 256 + (n0 & 127) + (mode - 1) * 128;
;         convert_tile(tile, src, N, kt * 64, n0, dst, K, drow); }
.LBB0_396:
	s_mul_hi_i32 s0, s2, 0x2fa0be83
	s_lshr_b32 s1, s0, 31
	s_ashr_i32 s0, s0, 4
	s_add_i32 s0, s0, s1
	s_mul_i32 s1, s0, 0xffffea80
	s_add_i32 s14, s5, s1
	s_mul_i32 s1, s0, 0xffffd500
	s_add_i32 s1, s7, s1
	s_and_b32 s1, s1, 0xffffff00
	s_and_b32 s13, s14, 64
	s_ashr_i32 s15, s14, 31
	s_or_b32 s1, s13, s1
	s_lshl_b32 s0, s0, 6
	s_waitcnt vmcnt(0)
	v_mov_b32_e32 v10, v226
	s_lshl_b64 s[14:15], s[14:15], 2
	s_add_u32 s14, s3, s14
	v_lshlrev_b32_e32 v0, 4, v10
	s_addc_u32 s15, s4, s15
	v_and_b32_e32 v0, 0xf0, v0
	v_ashrrev_i32_e32 v8, 4, v10
	v_lshl_add_u64 v[6:7], s[14:15], 0, v[0:1]
	v_add_u32_e32 v2, s0, v8
	v_mad_i64_i32 v[2:3], s[14:15], v2, s16, v[6:7]
	global_load_dwordx4 v[2:5], v[2:3], off
	v_add_u32_e32 v0, 0, v0
	v_mad_u64_u32 v[8:9], s[14:15], v8, s17, v[0:1]
	s_add_i32 s2, s2, s10
	s_add_i32 s5, s5, s6
	s_add_i32 s7, s7, s12
	v_add_u32_e32 v92, 0x200, v10
	v_ashrrev_i32_e32 v96, 4, v92
	v_add_u32_e32 v92, s0, v96
	v_mad_i64_i32 v[92:93], s[14:15], v92, s16, v[6:7]
	global_load_dwordx4 v[92:95], v[92:93], off
	v_mad_u64_u32 v[6:7], s[14:15], v96, s17, v[0:1]
	s_waitcnt vmcnt(1)
	ds_write2_b32 v8, v2, v3 offset1:1
	ds_write2_b32 v8, v4, v5 offset0:2 offset1:3
	v_ashrrev_i32_e32 v0, 3, v10
	s_waitcnt vmcnt(0)
	ds_write2_b32 v6, v92, v93 offset1:1
	ds_write2_b32 v6, v94, v95 offset0:2 offset1:3
	v_lshlrev_b32_e32 v2, 3, v10
	v_and_b32_e32 v10, 56, v2
	v_lshlrev_b32_e32 v2, 2, v0
	v_mul_u32_u24_e32 v3, 0x104, v10
	v_add3_u32 v6, 0, v2, v3
	s_waitcnt lgkmcnt(0)
	s_barrier
	ds_read2_b32 v[2:3], v6 offset1:65
	ds_read2_b32 v[4:5], v6 offset0:130 offset1:195
	v_add_u32_e32 v8, 0x400, v6
	ds_read2_b32 v[6:7], v8 offset0:4 offset1:69
	ds_read2_b32 v[8:9], v8 offset0:134 offset1:199
	s_waitcnt lgkmcnt(3)
	v_cvt_pk_bf16_f32 v2, v2, v3
	s_waitcnt lgkmcnt(2)
	v_cvt_pk_bf16_f32 v3, v4, v5
	s_waitcnt lgkmcnt(1)
	v_cvt_pk_bf16_f32 v4, v6, v7
	v_add_u32_e32 v6, s1, v0
	v_ashrrev_i32_e32 v7, 31, v6
	v_lshlrev_b64 v[6:7], 12, v[6:7]
	v_lshl_add_u64 v[6:7], s[98:99], 0, v[6:7]
	s_ashr_i32 s1, s0, 31
	v_lshl_add_u64 v[6:7], s[0:1], 1, v[6:7]
	v_lshlrev_b32_e32 v0, 1, v10
	s_waitcnt lgkmcnt(0)
	v_cvt_pk_bf16_f32 v5, v8, v9
	v_lshl_add_u64 v[6:7], v[6:7], 0, v[0:1]
	s_cmpk_lt_i32 s2, 0xac0
	global_store_dwordx4 v[6:7], v[2:5], off
	s_barrier
	s_cbranch_scc1 .LBB0_396

; #define LAS __attribute__((address_space(3)))
; __device__ __forceinline__ unsigned cvt_pk_bf16(float lo, float hi) { const f32x2 v = {lo, hi}; const bf16v2 r = __builtin_convertvector(v, bf16v2); return __builtin_bit_cast(unsigned, r); }
; __device__ __forceinline__ void convert_tile(LAS float* tile, const float* __restrict__ src, int N, int k0, int n0, bf16_t* __restrict__ dst, int K, int dst_row0) {
;     ...
;     for (int i = 0; i < 2; ++i) { const int idx = tid + 512 * i, k = idx >> 4, n4 = (idx & 15) * 4;
;         const f32x4 v = *(const f32x4*)(src + (size_t)(k0 + k) * N + n0 + n4);
;         tile[k * 65 + n4] = v[0]; tile[k * 65 + n4 + 1] = v[1]; tile[k * 65 + n4 + 2] = v[2]; tile[k * 65 + n4 + 3] = v[3]; }
;     __syncthreads();
;     { const int n = tid >> 3, kc = (tid & 7) * 8; float f[8];
; #pragma unroll
;       for (int j = 0; j < 8; ++j) f[j] = tile[(kc + j) * 65 + n];
;       u32x4 w; w.x = cvt_pk_bf16(f[0], f[1]); w.y = cvt_pk_bf16(f[2], f[3]); w.z = cvt_pk_bf16(f[4], f[5]); w.w = cvt_pk_bf16(f[6], f[7]);
;       *(u32x4*)(dst + (size_t)(dst_row0 + n) * K + k0 + kc) = w; }
;     __syncthreads();
; }
; __device__ void convert_mat(LAS float* tile, const float* src, int K, int N, bf16_t* dst, int mode, int rank, int stride) {
;     const int nnt = N / 64, nt = (K / 64) * nnt;
;     for (int t = rank; t < nt; t += stride) { const int kt = t / nnt, n0 = (t % nnt) * 64;
;         const int drow = mode == 0 ? n0 : (n0 >> 7) * 256 + (n0 & 127) + (mode - 1) * 128;
;         convert_tile(tile, src, N, kt * 64, n0, dst, K, drow); }
.LBB0_399:
	s_mul_hi_i32 s0, s2, 0x2fa0be83
	s_lshr_b32 s1, s0, 31
	s_ashr_i32 s0, s0, 4
	s_add_i32 s0, s0, s1
	s_mul_i32 s1, s0, 0xffffea80
	s_add_i32 s14, s5, s1
	s_and_b32 s1, s5, 64
	s_mul_i32 s13, s0, 0x2b00
	s_sub_i32 s1, s1, s13
	s_add_i32 s1, s7, s1
	s_ashr_i32 s15, s14, 31
	s_bitset1_b32 s1, 7
	s_lshl_b32 s0, s0, 6
	s_waitcnt vmcnt(0)
	v_mov_b32_e32 v10, v226
	s_lshl_b64 s[14:15], s[14:15], 2
	s_add_u32 s14, s3, s14
	v_lshlrev_b32_e32 v0, 4, v10
	s_addc_u32 s15, s4, s15
	v_and_b32_e32 v0, 0xf0, v0
	v_ashrrev_i32_e32 v8, 4, v10
	v_lshl_add_u64 v[6:7], s[14:15], 0, v[0:1]
	v_add_u32_e32 v2, s0, v8
	v_mad_i64_i32 v[2:3], s[14:15], v2, s16, v[6:7]
	global_load_dwordx4 v[2:5], v[2:3], off
	v_add_u32_e32 v0, 0, v0
	v_mad_u64_u32 v[8:9], s[14:15], v8, s17, v[0:1]
	s_add_i32 s2, s2, s10
	s_add_i32 s5, s5, s6
	s_add_i32 s7, s7, s12
	v_add_u32_e32 v92, 0x200, v10
	v_ashrrev_i32_e32 v96, 4, v92
	v_add_u32_e32 v92, s0, v96
	v_mad_i64_i32 v[92:93], s[14:15], v92, s16, v[6:7]
	global_load_dwordx4 v[92:95], v[92:93], off
	v_mad_u64_u32 v[6:7], s[14:15], v96, s17, v[0:1]
	s_waitcnt vmcnt(1)
	ds_write2_b32 v8, v2, v3 offset1:1
	ds_write2_b32 v8, v4, v5 offset0:2 offset1:3
	v_ashrrev_i32_e32 v0, 3, v10
	s_waitcnt vmcnt(0)
	ds_write2_b32 v6, v92, v93 offset1:1
	ds_write2_b32 v6, v94, v95 offset0:2 offset1:3
	v_lshlrev_b32_e32 v2, 3, v10
	v_and_b32_e32 v10, 56, v2
	v_lshlrev_b32_e32 v2, 2, v0
	v_mul_u32_u24_e32 v3, 0x104, v10
	v_add3_u32 v6, 0, v2, v3
	s_waitcnt lgkmcnt(0)
	s_barrier
	ds_read2_b32 v[2:3], v6 offset1:65
	ds_read2_b32 v[4:5], v6 offset0:130 offset1:195
	v_add_u32_e32 v8, 0x400, v6
	ds_read2_b32 v[6:7], v8 offset0:4 offset1:69
	ds_read2_b32 v[8:9], v8 offset0:134 offset1:199
	s_waitcnt lgkmcnt(3)
	v_cvt_pk_bf16_f32 v2, v2, v3
	s_waitcnt lgkmcnt(2)
	v_cvt_pk_bf16_f32 v3, v4, v5
	s_waitcnt lgkmcnt(1)
	v_cvt_pk_bf16_f32 v4, v6, v7
	v_add_u32_e32 v6, s1, v0
	v_ashrrev_i32_e32 v7, 31, v6
	v_lshlrev_b64 v[6:7], 12, v[6:7]
	v_lshl_add_u64 v[6:7], s[98:99], 0, v[6:7]
	s_ashr_i32 s1, s0, 31
	v_lshl_add_u64 v[6:7], s[0:1], 1, v[6:7]
	v_lshlrev_b32_e32 v0, 1, v10
	s_waitcnt lgkmcnt(0)
	v_cvt_pk_bf16_f32 v5, v8, v9
	v_lshl_add_u64 v[6:7], v[6:7], 0, v[0:1]
	s_cmpk_gt_i32 s2, 0xabf
	global_store_dwordx4 v[6:7], v[2:5], off
	s_barrier
	s_cbranch_scc0 .LBB0_399

;     __device__ bool next(int i, Unit& u) const {
;         const long L = (long)i * G + c; if (L >= nwg) return false;
;         int wgid = (int)L; { const int q = nwg / NXCD, r = nwg % NXCD, xcd = wgid % NXCD, off = wgid / NXCD; wgid = (xcd < r ? xcd * (q + 1) : r * (q + 1) + (xcd - r) * q) + off; }
;         const int nig = WGM * nN, gid = wgid / nig, fm = gid * WGM, gsz = (nM - fm) < WGM ? (nM - fm) : WGM;
;         u.pm = fm + ((wgid % nig) % gsz); u.pn = (wgid % nig) / gsz; return true;
;     }
; #pragma unroll
;     for (int t = 0; t < 8; ++t) s += ss[(size_t)t * T + row];
;     return rsqrtf(s * (1.0f / DM) + EPS); }
; __device__ __forceinline__ void gemm_phase(LAS unsigned char* lds, const Gemm g, const StaticOrder& S, const EpiAny& EA) {
;     ...
;         float rv[10]; bool ok[10];
; #pragma unroll
;         for (int s2 = 0; s2 < 10; ++s2) { const int i = 2 * s2 + (tid >> 8); Unit uu; ok[s2] = S.next(i, uu) && i < 19; rv[s2] = ok[s2] ? row_rstd(EA.ss, uu.pm * BM + (tid & 255)) : 0.f; }
; #pragma unroll
;         for (int s2 = 0; s2 < 10; ++s2) { const int i = 2 * s2 + (tid >> 8); if (ok[s2]) tab[i * 256 + (tid & 255)] = rv[s2]; }
;         __syncthreads();
.LBB0_425:
	s_cmp_eq_u64 s[28:29], 0
	s_mul_i32 s58, s23, 0x60
	s_cbranch_scc1 .LBB0_478
	s_waitcnt vmcnt(0)
	s_lshl_b32 s12, s23, 2
	s_lshr_b32 s13, s58, 3
	s_mov_b32 s24, 0x800000
	s_add_u32 s36, s28, 0x0
	s_addc_u32 s37, s29, 0
	s_add_u32 s38, s28, 0x18000
	s_addc_u32 s39, s29, 0
	s_add_u32 s40, s28, 0x30000
	s_addc_u32 s41, s29, 0
	s_add_u32 s42, s28, 0x48000
	s_addc_u32 s43, s29, 0
	s_add_u32 s44, s28, 0x60000
	s_addc_u32 s45, s29, 0
	s_add_u32 s46, s28, 0x78000
	s_addc_u32 s47, s29, 0
	s_add_u32 s48, s28, 0x90000
	s_addc_u32 s49, s29, 0
	s_add_u32 s50, s28, 0xa8000
	s_addc_u32 s51, s29, 0
	v_ashrrev_i32_e32 v14, 8, v0
	v_and_b32_e32 v15, 0xff, v0
	v_lshlrev_b32_e32 v15, 2, v15
	v_cvt_f32_u32_e32 v31, s12
	v_rcp_f32_e32 v31, v31
	v_mov_b32_e32 v32, s62
	v_add_u32_e32 v16, 0, v14
	v_mad_u32_u24 v33, v16, s10, v32
	v_and_b32_e32 v34, 7, v33
	v_lshrrev_b32_e32 v35, 3, v33
	v_mad_u32_u24 v34, v34, s13, v35
	v_cvt_f32_u32_e32 v35, v34
	v_add_f32_e32 v35, 0.5, v35
	v_mul_f32_e32 v35, v35, v31
	v_cvt_u32_f32_e32 v35, v35
	v_mul_u32_u24_e32 v36, s12, v35
	v_sub_u32_e32 v36, v34, v36
	v_and_b32_e32 v36, 3, v36
	v_lshl_add_u32 v36, v35, 2, v36
	v_lshl_add_u32 v36, v36, 10, v15
	v_cmp_gt_u32_e32 vcc, s58, v33
	s_nop 1
	v_cndmask_b32_e64 v26, 0, 1, vcc
	v_cmp_gt_u32_e32 vcc, 19, v16
	s_nop 1
	v_cndmask_b32_e32 v26, 0, v26, vcc
	v_cmp_eq_u32_e32 vcc, 1, v26
	s_nop 1
	v_cndmask_b32_e32 v21, v15, v36, vcc
	global_load_dword v42, v21, s[36:37]
	global_load_dword v43, v21, s[38:39]
	global_load_dword v44, v21, s[40:41]
	global_load_dword v45, v21, s[42:43]
	global_load_dword v46, v21, s[44:45]
	global_load_dword v47, v21, s[46:47]
	global_load_dword v48, v21, s[48:49]
	global_load_dword v49, v21, s[50:51]
	v_add_u32_e32 v17, 2, v14
	v_mad_u32_u24 v33, v17, s10, v32
	v_and_b32_e32 v34, 7, v33
	v_lshrrev_b32_e32 v35, 3, v33
	v_mad_u32_u24 v34, v34, s13, v35
	v_cvt_f32_u32_e32 v35, v34
	v_add_f32_e32 v35, 0.5, v35
	v_mul_f32_e32 v35, v35, v31
	v_cvt_u32_f32_e32 v35, v35
	v_mul_u32_u24_e32 v36, s12, v35
	v_sub_u32_e32 v36, v34, v36
	v_and_b32_e32 v36, 3, v36
	v_lshl_add_u32 v36, v35, 2, v36
	v_lshl_add_u32 v36, v36, 10, v15
	v_cmp_gt_u32_e32 vcc, s58, v33
	s_nop 1
	v_cndmask_b32_e64 v27, 0, 1, vcc
	v_cmp_gt_u32_e32 vcc, 19, v17
	s_nop 1
	v_cndmask_b32_e32 v27, 0, v27, vcc
	v_cmp_eq_u32_e32 vcc, 1, v27
	s_nop 1
	v_cndmask_b32_e32 v22, v15, v36, vcc
	global_load_dword v50, v22, s[36:37]
	global_load_dword v51, v22, s[38:39]
	global_load_dword v52, v22, s[40:41]
	global_load_dword v53, v22, s[42:43]
	global_load_dword v54, v22, s[44:45]
	global_load_dword v55, v22, s[46:47]
	global_load_dword v56, v22, s[48:49]
	global_load_dword v57, v22, s[50:51]
	v_add_u32_e32 v18, 4, v14
	v_mad_u32_u24 v33, v18, s10, v32
	v_and_b32_e32 v34, 7, v33
	v_lshrrev_b32_e32 v35, 3, v33
	v_mad_u32_u24 v34, v34, s13, v35
	v_cvt_f32_u32_e32 v35, v34
	v_add_f32_e32 v35, 0.5, v35
	v_mul_f32_e32 v35, v35, v31
	v_cvt_u32_f32_e32 v35, v35
	v_mul_u32_u24_e32 v36, s12, v35
	v_sub_u32_e32 v36, v34, v36
	v_and_b32_e32 v36, 3, v36
	v_lshl_add_u32 v36, v35, 2, v36
	v_lshl_add_u32 v36, v36, 10, v15
	v_cmp_gt_u32_e32 vcc, s58, v33
	s_nop 1
	v_cndmask_b32_e64 v28, 0, 1, vcc
	v_cmp_gt_u32_e32 vcc, 19, v18
	s_nop 1
	v_cndmask_b32_e32 v28, 0, v28, vcc
	v_cmp_eq_u32_e32 vcc, 1, v28
	s_nop 1
	v_cndmask_b32_e32 v23, v15, v36, vcc
	global_load_dword v58, v23, s[36:37]
	global_load_dword v59, v23, s[38:39]
	global_load_dword v60, v23, s[40:41]
	global_load_dword v61, v23, s[42:43]
	global_load_dword v62, v23, s[44:45]
	global_load_dword v63, v23, s[46:47]
	global_load_dword v64, v23, s[48:49]
	global_load_dword v65, v23, s[50:51]
	v_add_u32_e32 v19, 6, v14
	v_mad_u32_u24 v33, v19, s10, v32
	v_and_b32_e32 v34, 7, v33
	v_lshrrev_b32_e32 v35, 3, v33
	v_mad_u32_u24 v34, v34, s13, v35
	v_cvt_f32_u32_e32 v35, v34
	v_add_f32_e32 v35, 0.5, v35
	v_mul_f32_e32 v35, v35, v31
	v_cvt_u32_f32_e32 v35, v35
	v_mul_u32_u24_e32 v36, s12, v35
	v_sub_u32_e32 v36, v34, v36
	v_and_b32_e32 v36, 3, v36
	v_lshl_add_u32 v36, v35, 2, v36
	v_lshl_add_u32 v36, v36, 10, v15
	v_cmp_gt_u32_e32 vcc, s58, v33
	s_nop 1
	v_cndmask_b32_e64 v29, 0, 1, vcc
	v_cmp_gt_u32_e32 vcc, 19, v19
	s_nop 1
	v_cndmask_b32_e32 v29, 0, v29, vcc
	v_cmp_eq_u32_e32 vcc, 1, v29
	s_nop 1
	v_cndmask_b32_e32 v24, v15, v36, vcc
	global_load_dword v66, v24, s[36:37]
	global_load_dword v67, v24, s[38:39]
	global_load_dword v68, v24, s[40:41]
	global_load_dword v69, v24, s[42:43]
	global_load_dword v70, v24, s[44:45]
	global_load_dword v71, v24, s[46:47]
	global_load_dword v72, v24, s[48:49]
	global_load_dword v73, v24, s[50:51]
	v_add_u32_e32 v20, 8, v14
	v_mad_u32_u24 v33, v20, s10, v32
	v_and_b32_e32 v34, 7, v33
	v_lshrrev_b32_e32 v35, 3, v33
	v_mad_u32_u24 v34, v34, s13, v35
	v_cvt_f32_u32_e32 v35, v34
	v_add_f32_e32 v35, 0.5, v35
	v_mul_f32_e32 v35, v35, v31
	v_cvt_u32_f32_e32 v35, v35
	v_mul_u32_u24_e32 v36, s12, v35
	v_sub_u32_e32 v36, v34, v36
	v_and_b32_e32 v36, 3, v36
	v_lshl_add_u32 v36, v35, 2, v36
	v_lshl_add_u32 v36, v36, 10, v15
	v_cmp_gt_u32_e32 vcc, s58, v33
	s_nop 1
	v_cndmask_b32_e64 v30, 0, 1, vcc
	v_cmp_gt_u32_e32 vcc, 19, v20
	s_nop 1
	v_cndmask_b32_e32 v30, 0, v30, vcc
	v_cmp_eq_u32_e32 vcc, 1, v30
	s_nop 1
	v_cndmask_b32_e32 v25, v15, v36, vcc
	global_load_dword v74, v25, s[36:37]
	global_load_dword v75, v25, s[38:39]
	global_load_dword v76, v25, s[40:41]
	global_load_dword v77, v25, s[42:43]
	global_load_dword v78, v25, s[44:45]
	global_load_dword v79, v25, s[46:47]
	global_load_dword v80, v25, s[48:49]
	global_load_dword v81, v25, s[50:51]
	s_waitcnt vmcnt(0)
; #pragma unroll
;     for (int t = 0; t < 8; ++t) s += ss[(size_t)t * T + row];
;     return rsqrtf(s * (1.0f / DM) + EPS); }
; __device__ __forceinline__ void gemm_phase(LAS unsigned char* lds, const Gemm g, const StaticOrder& S, const EpiAny& EA) {
;     ...
;         for (int s2 = 0; s2 < 10; ++s2) { const int i = 2 * s2 + (tid >> 8); Unit uu; ok[s2] = S.next(i, uu) && i < 19; rv[s2] = ok[s2] ? row_rstd(EA.ss, uu.pm * BM + (tid & 255)) : 0.f; }
; #pragma unroll
;         for (int s2 = 0; s2 < 10; ++s2) { const int i = 2 * s2 + (tid >> 8); if (ok[s2]) tab[i * 256 + (tid & 255)] = rv[s2]; }
	v_add_f32_e32 v2, 0, v42
	v_add_f32_e32 v2, v2, v43
	v_add_f32_e32 v2, v2, v44
	v_add_f32_e32 v2, v2, v45
	v_add_f32_e32 v2, v2, v46
	v_add_f32_e32 v2, v2, v47
	v_add_f32_e32 v2, v2, v48
	v_add_f32_e32 v2, v2, v49
	v_fmamk_f32 v2, v2, 0x3a000000, v204
	v_mul_f32_e32 v3, 0x4b800000, v2
	v_cmp_gt_f32_e32 vcc, s24, v2
	s_nop 1
	v_cndmask_b32_e32 v2, v2, v3, vcc
	v_rsq_f32_e32 v2, v2
	s_nop 0
	v_mul_f32_e32 v3, 0x45800000, v2
	v_cndmask_b32_e32 v2, v2, v3, vcc
	v_lshl_add_u32 v3, v16, 10, v15
	v_add_u32_e32 v3, 0x21000, v3
	v_cmp_eq_u32_e32 vcc, 1, v26
	s_nop 1
	s_and_saveexec_b64 s[0:1], vcc
	ds_write_b32 v3, v2
	s_or_b64 exec, exec, s[0:1]
	v_add_f32_e32 v2, 0, v50
	v_add_f32_e32 v2, v2, v51
	v_add_f32_e32 v2, v2, v52
	v_add_f32_e32 v2, v2, v53
	v_add_f32_e32 v2, v2, v54
	v_add_f32_e32 v2, v2, v55
	v_add_f32_e32 v2, v2, v56
	v_add_f32_e32 v2, v2, v57
	v_fmamk_f32 v2, v2, 0x3a000000, v204
	v_mul_f32_e32 v3, 0x4b800000, v2
	v_cmp_gt_f32_e32 vcc, s24, v2
	s_nop 1
	v_cndmask_b32_e32 v2, v2, v3, vcc
	v_rsq_f32_e32 v2, v2
	s_nop 0
	v_mul_f32_e32 v3, 0x45800000, v2
	v_cndmask_b32_e32 v2, v2, v3, vcc
	v_lshl_add_u32 v3, v17, 10, v15
	v_add_u32_e32 v3, 0x21000, v3
	v_cmp_eq_u32_e32 vcc, 1, v27
	s_nop 1
	s_and_saveexec_b64 s[0:1], vcc
	ds_write_b32 v3, v2
	s_or_b64 exec, exec, s[0:1]
	v_add_f32_e32 v2, 0, v58
	v_add_f32_e32 v2, v2, v59
	v_add_f32_e32 v2, v2, v60
	v_add_f32_e32 v2, v2, v61
	v_add_f32_e32 v2, v2, v62
	v_add_f32_e32 v2, v2, v63
	v_add_f32_e32 v2, v2, v64
	v_add_f32_e32 v2, v2, v65
	v_fmamk_f32 v2, v2, 0x3a000000, v204
	v_mul_f32_e32 v3, 0x4b800000, v2
	v_cmp_gt_f32_e32 vcc, s24, v2
	s_nop 1
	v_cndmask_b32_e32 v2, v2, v3, vcc
	v_rsq_f32_e32 v2, v2
	s_nop 0
	v_mul_f32_e32 v3, 0x45800000, v2
	v_cndmask_b32_e32 v2, v2, v3, vcc
	v_lshl_add_u32 v3, v18, 10, v15
	v_add_u32_e32 v3, 0x21000, v3
	v_cmp_eq_u32_e32 vcc, 1, v28
	s_nop 1
	s_and_saveexec_b64 s[0:1], vcc
	ds_write_b32 v3, v2
	s_or_b64 exec, exec, s[0:1]
	v_add_f32_e32 v2, 0, v66
	v_add_f32_e32 v2, v2, v67
	v_add_f32_e32 v2, v2, v68
	v_add_f32_e32 v2, v2, v69
	v_add_f32_e32 v2, v2, v70
	v_add_f32_e32 v2, v2, v71
	v_add_f32_e32 v2, v2, v72
	v_add_f32_e32 v2, v2, v73
	v_fmamk_f32 v2, v2, 0x3a000000, v204
	v_mul_f32_e32 v3, 0x4b800000, v2
	v_cmp_gt_f32_e32 vcc, s24, v2
	s_nop 1
	v_cndmask_b32_e32 v2, v2, v3, vcc
	v_rsq_f32_e32 v2, v2
	s_nop 0
	v_mul_f32_e32 v3, 0x45800000, v2
	v_cndmask_b32_e32 v2, v2, v3, vcc
	v_lshl_add_u32 v3, v19, 10, v15
	v_add_u32_e32 v3, 0x21000, v3
	v_cmp_eq_u32_e32 vcc, 1, v29
	s_nop 1
	s_and_saveexec_b64 s[0:1], vcc
	ds_write_b32 v3, v2
	s_or_b64 exec, exec, s[0:1]
	v_add_f32_e32 v2, 0, v74
	v_add_f32_e32 v2, v2, v75
	v_add_f32_e32 v2, v2, v76
	v_add_f32_e32 v2, v2, v77
	v_add_f32_e32 v2, v2, v78
	v_add_f32_e32 v2, v2, v79
	v_add_f32_e32 v2, v2, v80
	v_add_f32_e32 v2, v2, v81
	v_fmamk_f32 v2, v2, 0x3a000000, v204
	v_mul_f32_e32 v3, 0x4b800000, v2
	v_cmp_gt_f32_e32 vcc, s24, v2
	s_nop 1
	v_cndmask_b32_e32 v2, v2, v3, vcc
	v_rsq_f32_e32 v2, v2
	s_nop 0
	v_mul_f32_e32 v3, 0x45800000, v2
	v_cndmask_b32_e32 v2, v2, v3, vcc
	v_lshl_add_u32 v3, v20, 10, v15
	v_add_u32_e32 v3, 0x21000, v3
	v_cmp_eq_u32_e32 vcc, 1, v30
	s_nop 1
	s_and_saveexec_b64 s[0:1], vcc
	ds_write_b32 v3, v2
	s_or_b64 exec, exec, s[0:1]
	v_add_u32_e32 v16, 10, v14
	v_mad_u32_u24 v33, v16, s10, v32
	v_and_b32_e32 v34, 7, v33
	v_lshrrev_b32_e32 v35, 3, v33
	v_mad_u32_u24 v34, v34, s13, v35
	v_cvt_f32_u32_e32 v35, v34
	v_add_f32_e32 v35, 0.5, v35
	v_mul_f32_e32 v35, v35, v31
	v_cvt_u32_f32_e32 v35, v35
	v_mul_u32_u24_e32 v36, s12, v35
	v_sub_u32_e32 v36, v34, v36
	v_and_b32_e32 v36, 3, v36
	v_lshl_add_u32 v36, v35, 2, v36
	v_lshl_add_u32 v36, v36, 10, v15
	v_cmp_gt_u32_e32 vcc, s58, v33
	s_nop 1
	v_cndmask_b32_e64 v26, 0, 1, vcc
	v_cmp_gt_u32_e32 vcc, 19, v16
	s_nop 1
	v_cndmask_b32_e32 v26, 0, v26, vcc
	v_cmp_eq_u32_e32 vcc, 1, v26
	s_nop 1
	v_cndmask_b32_e32 v21, v15, v36, vcc
	global_load_dword v42, v21, s[36:37]
	global_load_dword v43, v21, s[38:39]
	global_load_dword v44, v21, s[40:41]
	global_load_dword v45, v21, s[42:43]
	global_load_dword v46, v21, s[44:45]
	global_load_dword v47, v21, s[46:47]
	global_load_dword v48, v21, s[48:49]
	global_load_dword v49, v21, s[50:51]
	v_add_u32_e32 v17, 12, v14
	v_mad_u32_u24 v33, v17, s10, v32
	v_and_b32_e32 v34, 7, v33
	v_lshrrev_b32_e32 v35, 3, v33
	v_mad_u32_u24 v34, v34, s13, v35
	v_cvt_f32_u32_e32 v35, v34
	v_add_f32_e32 v35, 0.5, v35
	v_mul_f32_e32 v35, v35, v31
	v_cvt_u32_f32_e32 v35, v35
	v_mul_u32_u24_e32 v36, s12, v35
	v_sub_u32_e32 v36, v34, v36
	v_and_b32_e32 v36, 3, v36
	v_lshl_add_u32 v36, v35, 2, v36
	v_lshl_add_u32 v36, v36, 10, v15
	v_cmp_gt_u32_e32 vcc, s58, v33
	s_nop 1
	v_cndmask_b32_e64 v27, 0, 1, vcc
	v_cmp_gt_u32_e32 vcc, 19, v17
	s_nop 1
	v_cndmask_b32_e32 v27, 0, v27, vcc
	v_cmp_eq_u32_e32 vcc, 1, v27
	s_nop 1
	v_cndmask_b32_e32 v22, v15, v36, vcc
	global_load_dword v50, v22, s[36:37]
	global_load_dword v51, v22, s[38:39]
	global_load_dword v52, v22, s[40:41]
	global_load_dword v53, v22, s[42:43]
	global_load_dword v54, v22, s[44:45]
	global_load_dword v55, v22, s[46:47]
	global_load_dword v56, v22, s[48:49]
	global_load_dword v57, v22, s[50:51]
	v_add_u32_e32 v18, 14, v14
	v_mad_u32_u24 v33, v18, s10, v32
	v_and_b32_e32 v34, 7, v33
	v_lshrrev_b32_e32 v35, 3, v33
	v_mad_u32_u24 v34, v34, s13, v35
	v_cvt_f32_u32_e32 v35, v34
	v_add_f32_e32 v35, 0.5, v35
	v_mul_f32_e32 v35, v35, v31
	v_cvt_u32_f32_e32 v35, v35
	v_mul_u32_u24_e32 v36, s12, v35
	v_sub_u32_e32 v36, v34, v36
	v_and_b32_e32 v36, 3, v36
	v_lshl_add_u32 v36, v35, 2, v36
	v_lshl_add_u32 v36, v36, 10, v15
	v_cmp_gt_u32_e32 vcc, s58, v33
	s_nop 1
	v_cndmask_b32_e64 v28, 0, 1, vcc
; #pragma unroll
;     for (int t = 0; t < 8; ++t) s += ss[(size_t)t * T + row];
;     return rsqrtf(s * (1.0f / DM) + EPS); }
; __device__ __forceinline__ void gemm_phase(LAS unsigned char* lds, const Gemm g, const StaticOrder& S, const EpiAny& EA) {
;     ...
;         for (int s2 = 0; s2 < 10; ++s2) { const int i = 2 * s2 + (tid >> 8); Unit uu; ok[s2] = S.next(i, uu) && i < 19; rv[s2] = ok[s2] ? row_rstd(EA.ss, uu.pm * BM + (tid & 255)) : 0.f; }
; #pragma unroll
;         for (int s2 = 0; s2 < 10; ++s2) { const int i = 2 * s2 + (tid >> 8); if (ok[s2]) tab[i * 256 + (tid & 255)] = rv[s2]; }
;         __syncthreads();
	v_cmp_gt_u32_e32 vcc, 19, v18
	s_nop 1
	v_cndmask_b32_e32 v28, 0, v28, vcc
	v_cmp_eq_u32_e32 vcc, 1, v28
	s_nop 1
	v_cndmask_b32_e32 v23, v15, v36, vcc
	global_load_dword v58, v23, s[36:37]
	global_load_dword v59, v23, s[38:39]
	global_load_dword v60, v23, s[40:41]
	global_load_dword v61, v23, s[42:43]
	global_load_dword v62, v23, s[44:45]
	global_load_dword v63, v23, s[46:47]
	global_load_dword v64, v23, s[48:49]
	global_load_dword v65, v23, s[50:51]
	v_add_u32_e32 v19, 16, v14
	v_mad_u32_u24 v33, v19, s10, v32
	v_and_b32_e32 v34, 7, v33
	v_lshrrev_b32_e32 v35, 3, v33
	v_mad_u32_u24 v34, v34, s13, v35
	v_cvt_f32_u32_e32 v35, v34
	v_add_f32_e32 v35, 0.5, v35
	v_mul_f32_e32 v35, v35, v31
	v_cvt_u32_f32_e32 v35, v35
	v_mul_u32_u24_e32 v36, s12, v35
	v_sub_u32_e32 v36, v34, v36
	v_and_b32_e32 v36, 3, v36
	v_lshl_add_u32 v36, v35, 2, v36
	v_lshl_add_u32 v36, v36, 10, v15
	v_cmp_gt_u32_e32 vcc, s58, v33
	s_nop 1
	v_cndmask_b32_e64 v29, 0, 1, vcc
	v_cmp_gt_u32_e32 vcc, 19, v19
	s_nop 1
	v_cndmask_b32_e32 v29, 0, v29, vcc
	v_cmp_eq_u32_e32 vcc, 1, v29
	s_nop 1
	v_cndmask_b32_e32 v24, v15, v36, vcc
	global_load_dword v66, v24, s[36:37]
	global_load_dword v67, v24, s[38:39]
	global_load_dword v68, v24, s[40:41]
	global_load_dword v69, v24, s[42:43]
	global_load_dword v70, v24, s[44:45]
	global_load_dword v71, v24, s[46:47]
	global_load_dword v72, v24, s[48:49]
	global_load_dword v73, v24, s[50:51]
	v_add_u32_e32 v20, 18, v14
	v_mad_u32_u24 v33, v20, s10, v32
	v_and_b32_e32 v34, 7, v33
	v_lshrrev_b32_e32 v35, 3, v33
	v_mad_u32_u24 v34, v34, s13, v35
	v_cvt_f32_u32_e32 v35, v34
	v_add_f32_e32 v35, 0.5, v35
	v_mul_f32_e32 v35, v35, v31
	v_cvt_u32_f32_e32 v35, v35
	v_mul_u32_u24_e32 v36, s12, v35
	v_sub_u32_e32 v36, v34, v36
	v_and_b32_e32 v36, 3, v36
	v_lshl_add_u32 v36, v35, 2, v36
	v_lshl_add_u32 v36, v36, 10, v15
	v_cmp_gt_u32_e32 vcc, s58, v33
	s_nop 1
	v_cndmask_b32_e64 v30, 0, 1, vcc
	v_cmp_gt_u32_e32 vcc, 19, v20
	s_nop 1
	v_cndmask_b32_e32 v30, 0, v30, vcc
	v_cmp_eq_u32_e32 vcc, 1, v30
	s_nop 1
	v_cndmask_b32_e32 v25, v15, v36, vcc
	global_load_dword v74, v25, s[36:37]
	global_load_dword v75, v25, s[38:39]
	global_load_dword v76, v25, s[40:41]
	global_load_dword v77, v25, s[42:43]
	global_load_dword v78, v25, s[44:45]
	global_load_dword v79, v25, s[46:47]
	global_load_dword v80, v25, s[48:49]
	global_load_dword v81, v25, s[50:51]
	s_waitcnt vmcnt(0)
	v_add_f32_e32 v2, 0, v42
	v_add_f32_e32 v2, v2, v43
	v_add_f32_e32 v2, v2, v44
	v_add_f32_e32 v2, v2, v45
	v_add_f32_e32 v2, v2, v46
	v_add_f32_e32 v2, v2, v47
	v_add_f32_e32 v2, v2, v48
	v_add_f32_e32 v2, v2, v49
	v_fmamk_f32 v2, v2, 0x3a000000, v204
	v_mul_f32_e32 v3, 0x4b800000, v2
	v_cmp_gt_f32_e32 vcc, s24, v2
	s_nop 1
	v_cndmask_b32_e32 v2, v2, v3, vcc
	v_rsq_f32_e32 v2, v2
	s_nop 0
	v_mul_f32_e32 v3, 0x45800000, v2
	v_cndmask_b32_e32 v2, v2, v3, vcc
	v_lshl_add_u32 v3, v16, 10, v15
	v_add_u32_e32 v3, 0x21000, v3
	v_cmp_eq_u32_e32 vcc, 1, v26
	s_nop 1
	s_and_saveexec_b64 s[0:1], vcc
	ds_write_b32 v3, v2
	s_or_b64 exec, exec, s[0:1]
	v_add_f32_e32 v2, 0, v50
	v_add_f32_e32 v2, v2, v51
	v_add_f32_e32 v2, v2, v52
	v_add_f32_e32 v2, v2, v53
	v_add_f32_e32 v2, v2, v54
	v_add_f32_e32 v2, v2, v55
	v_add_f32_e32 v2, v2, v56
	v_add_f32_e32 v2, v2, v57
	v_fmamk_f32 v2, v2, 0x3a000000, v204
	v_mul_f32_e32 v3, 0x4b800000, v2
	v_cmp_gt_f32_e32 vcc, s24, v2
	s_nop 1
	v_cndmask_b32_e32 v2, v2, v3, vcc
	v_rsq_f32_e32 v2, v2
	s_nop 0
	v_mul_f32_e32 v3, 0x45800000, v2
	v_cndmask_b32_e32 v2, v2, v3, vcc
	v_lshl_add_u32 v3, v17, 10, v15
	v_add_u32_e32 v3, 0x21000, v3
	v_cmp_eq_u32_e32 vcc, 1, v27
	s_nop 1
	s_and_saveexec_b64 s[0:1], vcc
	ds_write_b32 v3, v2
	s_or_b64 exec, exec, s[0:1]
	v_add_f32_e32 v2, 0, v58
	v_add_f32_e32 v2, v2, v59
	v_add_f32_e32 v2, v2, v60
	v_add_f32_e32 v2, v2, v61
	v_add_f32_e32 v2, v2, v62
	v_add_f32_e32 v2, v2, v63
	v_add_f32_e32 v2, v2, v64
	v_add_f32_e32 v2, v2, v65
	v_fmamk_f32 v2, v2, 0x3a000000, v204
	v_mul_f32_e32 v3, 0x4b800000, v2
	v_cmp_gt_f32_e32 vcc, s24, v2
	s_nop 1
	v_cndmask_b32_e32 v2, v2, v3, vcc
	v_rsq_f32_e32 v2, v2
	s_nop 0
	v_mul_f32_e32 v3, 0x45800000, v2
	v_cndmask_b32_e32 v2, v2, v3, vcc
	v_lshl_add_u32 v3, v18, 10, v15
	v_add_u32_e32 v3, 0x21000, v3
	v_cmp_eq_u32_e32 vcc, 1, v28
	s_nop 1
	s_and_saveexec_b64 s[0:1], vcc
	ds_write_b32 v3, v2
	s_or_b64 exec, exec, s[0:1]
	v_add_f32_e32 v2, 0, v66
	v_add_f32_e32 v2, v2, v67
	v_add_f32_e32 v2, v2, v68
	v_add_f32_e32 v2, v2, v69
	v_add_f32_e32 v2, v2, v70
	v_add_f32_e32 v2, v2, v71
	v_add_f32_e32 v2, v2, v72
	v_add_f32_e32 v2, v2, v73
	v_fmamk_f32 v2, v2, 0x3a000000, v204
	v_mul_f32_e32 v3, 0x4b800000, v2
	v_cmp_gt_f32_e32 vcc, s24, v2
	s_nop 1
	v_cndmask_b32_e32 v2, v2, v3, vcc
	v_rsq_f32_e32 v2, v2
	s_nop 0
	v_mul_f32_e32 v3, 0x45800000, v2
	v_cndmask_b32_e32 v2, v2, v3, vcc
	v_lshl_add_u32 v3, v19, 10, v15
	v_add_u32_e32 v3, 0x21000, v3
	v_cmp_eq_u32_e32 vcc, 1, v29
	s_nop 1
	s_and_saveexec_b64 s[0:1], vcc
	ds_write_b32 v3, v2
	s_or_b64 exec, exec, s[0:1]
	v_add_f32_e32 v2, 0, v74
	v_add_f32_e32 v2, v2, v75
	v_add_f32_e32 v2, v2, v76
	v_add_f32_e32 v2, v2, v77
	v_add_f32_e32 v2, v2, v78
	v_add_f32_e32 v2, v2, v79
	v_add_f32_e32 v2, v2, v80
	v_add_f32_e32 v2, v2, v81
	v_fmamk_f32 v2, v2, 0x3a000000, v204
	v_mul_f32_e32 v3, 0x4b800000, v2
	v_cmp_gt_f32_e32 vcc, s24, v2
	s_nop 1
	v_cndmask_b32_e32 v2, v2, v3, vcc
	v_rsq_f32_e32 v2, v2
	s_nop 0
	v_mul_f32_e32 v3, 0x45800000, v2
	v_cndmask_b32_e32 v2, v2, v3, vcc
	v_lshl_add_u32 v3, v20, 10, v15
	v_add_u32_e32 v3, 0x21000, v3
	v_cmp_eq_u32_e32 vcc, 1, v30
	s_nop 1
	s_and_saveexec_b64 s[0:1], vcc
	ds_write_b32 v3, v2
	s_or_b64 exec, exec, s[0:1]
	s_waitcnt lgkmcnt(0)
	s_barrier
; #define LAS __attribute__((address_space(3)))
;     __device__ bool next(int i, Unit& u) const {
;         const long L = (long)i * G + c; if (L >= nwg) return false;
;         int wgid = (int)L; { const int q = nwg / NXCD, r = nwg % NXCD, xcd = wgid % NXCD, off = wgid / NXCD; wgid = (xcd < r ? xcd * (q + 1) : r * (q + 1) + (xcd - r) * q) + off; }
;         const int nig = WGM * nN, gid = wgid / nig, fm = gid * WGM, gsz = (nM - fm) < WGM ? (nM - fm) : WGM;
;         u.pm = fm + ((wgid % nig) % gsz); u.pn = (wgid % nig) / gsz; return true;
; __device__ __forceinline__ void gemm_phase(LAS unsigned char* lds, const Gemm g, const StaticOrder& S, const EpiAny& EA) {
;     ...
;     if (EA.ss) {
;         LAS float* tab = (LAS float*)(lds + LDS_RSL);
;         float rv[10]; bool ok[10];
; #pragma unroll
;         for (int s2 = 0; s2 < 10; ++s2) { const int i = 2 * s2 + (tid >> 8); Unit uu; ok[s2] = S.next(i, uu) && i < 19; rv[s2] = ok[s2] ? row_rstd(EA.ss, uu.pm * BM + (tid & 255)) : 0.f; }
; #pragma unroll
;         for (int s2 = 0; s2 < 10; ++s2) { const int i = 2 * s2 + (tid >> 8); if (ok[s2]) tab[i * 256 + (tid & 255)] = rv[s2]; }
	s_branch .LBB0_478
	s_lshl_b32 s12, s23, 2
	s_waitcnt vmcnt(0)
	v_cvt_f32_u32_e32 v15, s12
	s_ashr_i32 s63, s62, 31
	v_ashrrev_i32_e32 v14, 8, v0
	v_mov_b64_e32 v[2:3], s[62:63]
	v_rcp_iflag_f32_e32 v16, v15
	s_mov_b32 s59, s61
	s_lshr_b32 s13, s58, 3
	v_mad_i64_i32 v[2:3], s[0:1], v14, s10, v[2:3]
	s_or_b32 s18, s13, 1
	v_cmp_gt_i64_e32 vcc, s[58:59], v[2:3]
	s_and_saveexec_b64 s[36:37], vcc
	s_cbranch_execz .LBB0_428
	v_ashrrev_i32_e32 v3, 31, v2
	v_lshrrev_b32_e32 v3, 29, v3
	v_add_u32_e32 v3, v2, v3
	v_ashrrev_i32_e32 v15, 3, v3
	v_and_b32_e32 v3, -8, v3
	v_sub_u32_e32 v2, v2, v3
	v_mov_b32_e32 v3, s13
	v_mov_b32_e32 v17, s18
	v_cmp_gt_i32_e64 s[0:1], 0, v2
	s_nop 1
	v_cndmask_b32_e64 v3, v3, v17, s[0:1]
	v_mul_lo_u32 v2, v3, v2
	v_add_u32_e32 v2, v2, v15
	v_mul_f32_e32 v15, 0x4f7ffffe, v16
	v_cvt_u32_f32_e32 v15, v15
	s_sub_i32 s0, 0, s12
	v_sub_u32_e32 v17, 0, v2
	v_max_i32_e32 v17, v2, v17
	s_waitcnt vmcnt(0)
	v_mul_lo_u32 v18, s0, v15
	v_mul_hi_u32 v18, v15, v18
	v_add_u32_e32 v15, v15, v18
	v_mul_hi_u32 v15, v17, v15
	v_mul_lo_u32 v18, v15, s12
	v_sub_u32_e32 v17, v17, v18
	v_add_u32_e32 v18, 1, v15
	v_cmp_le_u32_e64 s[0:1], s12, v17
	v_ashrrev_i32_e32 v3, 31, v2
	s_nop 0
	v_cndmask_b32_e64 v15, v15, v18, s[0:1]
	v_subrev_u32_e32 v18, s12, v17
	v_cndmask_b32_e64 v17, v17, v18, s[0:1]
	v_add_u32_e32 v18, 1, v15
	v_cmp_le_u32_e64 s[0:1], s12, v17
	s_nop 1
	v_cndmask_b32_e64 v15, v15, v18, s[0:1]
	v_xor_b32_e32 v15, v15, v3
	v_sub_u32_e32 v3, v15, v3
	v_lshlrev_b32_e32 v15, 2, v3
	v_sub_u32_e32 v17, 0x60, v15
	v_min_i32_e32 v17, 4, v17
	v_sub_u32_e32 v18, 0, v17
	v_max_i32_e32 v17, v17, v18
	v_cvt_f32_u32_e32 v18, v17
	v_mul_lo_u32 v3, v3, s12
	v_sub_u32_e32 v2, v2, v3
	v_sub_u32_e32 v19, 0, v2
	v_rcp_iflag_f32_e32 v18, v18
	v_ashrrev_i32_e32 v3, 31, v2
	v_max_i32_e32 v2, v2, v19
	v_sub_u32_e32 v19, 0, v17
	v_mul_f32_e32 v18, 0x4f7ffffe, v18
	v_cvt_u32_f32_e32 v18, v18
	v_mul_lo_u32 v19, v19, v18
	v_mul_hi_u32 v19, v18, v19
	v_add_u32_e32 v18, v18, v19
	v_mul_hi_u32 v18, v2, v18
	v_mul_lo_u32 v18, v18, v17
	v_sub_u32_e32 v2, v2, v18
	v_sub_u32_e32 v18, v2, v17
	v_cmp_ge_u32_e64 s[0:1], v2, v17
	s_nop 1
	v_cndmask_b32_e64 v2, v2, v18, s[0:1]
	v_sub_u32_e32 v18, v2, v17
	v_cmp_ge_u32_e64 s[0:1], v2, v17
	s_nop 1
	v_cndmask_b32_e64 v2, v2, v18, s[0:1]
	v_xor_b32_e32 v2, v2, v3
	v_sub_u32_e32 v2, v2, v3
	v_add_u32_e32 v21, v2, v15

; #define LAS __attribute__((address_space(3)))
; __device__ __forceinline__ unsigned cvt_pk_bf16(float lo, float hi) { const f32x2 v = {lo, hi}; const bf16v2 r = __builtin_convertvector(v, bf16v2); return __builtin_bit_cast(unsigned, r); }
; __device__ __forceinline__ void convert_tile(LAS float* tile, const float* __restrict__ src, int N, int k0, int n0, bf16_t* __restrict__ dst, int K, int dst_row0) {
;     ...
;     for (int i = 0; i < 2; ++i) { const int idx = tid + 512 * i, k = idx >> 4, n4 = (idx & 15) * 4;
;         const f32x4 v = *(const f32x4*)(src + (size_t)(k0 + k) * N + n0 + n4);
;         tile[k * 65 + n4] = v[0]; tile[k * 65 + n4 + 1] = v[1]; tile[k * 65 + n4 + 2] = v[2]; tile[k * 65 + n4 + 3] = v[3]; }
;     __syncthreads();
;     { const int n = tid >> 3, kc = (tid & 7) * 8; float f[8];
; #pragma unroll
;       for (int j = 0; j < 8; ++j) f[j] = tile[(kc + j) * 65 + n];
;       u32x4 w; w.x = cvt_pk_bf16(f[0], f[1]); w.y = cvt_pk_bf16(f[2], f[3]); w.z = cvt_pk_bf16(f[4], f[5]); w.w = cvt_pk_bf16(f[6], f[7]);
;       *(u32x4*)(dst + (size_t)(dst_row0 + n) * K + k0 + kc) = w; }
;     __syncthreads();
; }
; __device__ void convert_mat(LAS float* tile, const float* src, int K, int N, bf16_t* dst, int mode, int rank, int stride) {
;     const int nnt = N / 64, nt = (K / 64) * nnt;
;     for (int t = rank; t < nt; t += stride) { const int kt = t / nnt, n0 = (t % nnt) * 64;
;         const int drow = mode == 0 ? n0 : (n0 >> 7) * 256 + (n0 & 127) + (mode - 1) * 128;
;         convert_tile(tile, src, N, kt * 64, n0, dst, K, drow); }
.LBB0_684:
	s_ashr_i32 s0, s12, 31
	s_lshr_b32 s0, s0, 27
	s_add_i32 s0, s12, s0
	s_ashr_i32 s0, s0, 5
	s_lshl_b32 s1, s0, 11
	s_sub_i32 s14, s6, s1
	v_mov_b32_e32 v10, v226
	s_ashr_i32 s15, s14, 31
	s_lshl_b32 s0, s0, 6
	s_lshl_b64 s[14:15], s[14:15], 2
	v_ashrrev_i32_e32 v8, 4, v10
	s_add_u32 s14, s4, s14
	v_lshlrev_b32_e32 v0, 4, v10
	v_add_u32_e32 v2, s0, v8
	s_addc_u32 s15, s5, s15
	v_and_b32_e32 v0, 0xf0, v0
	v_ashrrev_i32_e32 v3, 31, v2
	v_lshl_add_u64 v[6:7], s[14:15], 0, v[0:1]
	v_lshlrev_b64 v[2:3], 13, v[2:3]
	v_lshl_add_u64 v[2:3], v[6:7], 0, v[2:3]
	global_load_dwordx4 v[2:5], v[2:3], off
	v_add_u32_e32 v0, 0, v0
	v_mad_u64_u32 v[8:9], s[14:15], v8, s18, v[0:1]
	s_add_i32 s12, s12, s3
	v_add_u32_e32 v92, 0x200, v10
	v_ashrrev_i32_e32 v96, 4, v92
	v_add_u32_e32 v92, s0, v96
	v_ashrrev_i32_e32 v93, 31, v92
	v_lshlrev_b64 v[92:93], 13, v[92:93]
	v_lshl_add_u64 v[92:93], v[6:7], 0, v[92:93]
	global_load_dwordx4 v[92:95], v[92:93], off
	v_mad_u64_u32 v[6:7], s[14:15], v96, s18, v[0:1]
	s_waitcnt vmcnt(1)
	ds_write2_b32 v8, v2, v3 offset1:1
	ds_write2_b32 v8, v4, v5 offset0:2 offset1:3
	v_ashrrev_i32_e32 v0, 3, v10
	s_waitcnt vmcnt(0)
	ds_write2_b32 v6, v92, v93 offset1:1
	ds_write2_b32 v6, v94, v95 offset0:2 offset1:3
	v_lshlrev_b32_e32 v2, 3, v10
	v_and_b32_e32 v10, 56, v2
	v_lshlrev_b32_e32 v2, 2, v0
	v_mul_u32_u24_e32 v3, 0x104, v10
	v_add3_u32 v6, 0, v2, v3
	s_waitcnt lgkmcnt(0)
	s_barrier
	ds_read2_b32 v[2:3], v6 offset1:65
	ds_read2_b32 v[4:5], v6 offset0:130 offset1:195
	v_add_u32_e32 v8, 0x400, v6
	ds_read2_b32 v[6:7], v8 offset0:4 offset1:69
	ds_read2_b32 v[8:9], v8 offset0:134 offset1:199
	v_subrev_u32_e32 v0, s1, v0
	s_waitcnt lgkmcnt(3)
	v_cvt_pk_bf16_f32 v2, v2, v3
	s_waitcnt lgkmcnt(2)
	v_cvt_pk_bf16_f32 v3, v4, v5
	s_waitcnt lgkmcnt(1)
	v_cvt_pk_bf16_f32 v4, v6, v7
	v_add_u32_e32 v0, s6, v0
	v_mov_b64_e32 v[6:7], s[86:87]
	v_mad_i64_i32 v[6:7], s[14:15], v0, s13, v[6:7]
	s_ashr_i32 s1, s0, 31
	v_lshl_add_u64 v[6:7], s[0:1], 1, v[6:7]
	v_lshlrev_b32_e32 v0, 1, v10
	s_add_i32 s6, s6, s7
	s_waitcnt lgkmcnt(0)
	v_cvt_pk_bf16_f32 v5, v8, v9
	v_lshl_add_u64 v[6:7], v[6:7], 0, v[0:1]
	s_cmpk_gt_i32 s12, 0xabf
	global_store_dwordx4 v[6:7], v[2:5], off
	s_barrier
	s_cbranch_scc0 .LBB0_684

; #define LAS __attribute__((address_space(3)))
; __device__ __forceinline__ unsigned cvt_pk_bf16(float lo, float hi) { const f32x2 v = {lo, hi}; const bf16v2 r = __builtin_convertvector(v, bf16v2); return __builtin_bit_cast(unsigned, r); }
; __device__ __forceinline__ void convert_tile(LAS float* tile, const float* __restrict__ src, int N, int k0, int n0, bf16_t* __restrict__ dst, int K, int dst_row0) {
;     ...
;     for (int i = 0; i < 2; ++i) { const int idx = tid + 512 * i, k = idx >> 4, n4 = (idx & 15) * 4;
;         const f32x4 v = *(const f32x4*)(src + (size_t)(k0 + k) * N + n0 + n4);
;         tile[k * 65 + n4] = v[0]; tile[k * 65 + n4 + 1] = v[1]; tile[k * 65 + n4 + 2] = v[2]; tile[k * 65 + n4 + 3] = v[3]; }
;     __syncthreads();
;     { const int n = tid >> 3, kc = (tid & 7) * 8; float f[8];
; #pragma unroll
;       for (int j = 0; j < 8; ++j) f[j] = tile[(kc + j) * 65 + n];
;       u32x4 w; w.x = cvt_pk_bf16(f[0], f[1]); w.y = cvt_pk_bf16(f[2], f[3]); w.z = cvt_pk_bf16(f[4], f[5]); w.w = cvt_pk_bf16(f[6], f[7]);
;       *(u32x4*)(dst + (size_t)(dst_row0 + n) * K + k0 + kc) = w; }
;     __syncthreads();
; }
; __device__ void convert_mat(LAS float* tile, const float* src, int K, int N, bf16_t* dst, int mode, int rank, int stride) {
;     const int nnt = N / 64, nt = (K / 64) * nnt;
;     for (int t = rank; t < nt; t += stride) { const int kt = t / nnt, n0 = (t % nnt) * 64;
;         const int drow = mode == 0 ? n0 : (n0 >> 7) * 256 + (n0 & 127) + (mode - 1) * 128;
;         convert_tile(tile, src, N, kt * 64, n0, dst, K, drow); }
.LBB0_689:
	s_ashr_i32 s0, s12, 31
	s_lshr_b32 s0, s0, 27
	s_add_i32 s0, s12, s0
	s_ashr_i32 s0, s0, 5
	s_lshl_b32 s1, s0, 11
	s_sub_i32 s14, s6, s1
	v_mov_b32_e32 v10, v226
	s_ashr_i32 s15, s14, 31
	s_lshl_b32 s0, s0, 6
	s_lshl_b64 s[14:15], s[14:15], 2
	v_ashrrev_i32_e32 v8, 4, v10
	s_add_u32 s14, s4, s14
	v_lshlrev_b32_e32 v0, 4, v10
	v_add_u32_e32 v2, s0, v8
	s_addc_u32 s15, s5, s15
	v_and_b32_e32 v0, 0xf0, v0
	v_ashrrev_i32_e32 v3, 31, v2
	v_lshl_add_u64 v[6:7], s[14:15], 0, v[0:1]
	v_lshlrev_b64 v[2:3], 13, v[2:3]
	v_lshl_add_u64 v[2:3], v[6:7], 0, v[2:3]
	global_load_dwordx4 v[2:5], v[2:3], off
	v_add_u32_e32 v0, 0, v0
	v_mad_u64_u32 v[8:9], s[14:15], v8, s18, v[0:1]
	s_add_i32 s12, s12, s3
	v_add_u32_e32 v92, 0x200, v10
	v_ashrrev_i32_e32 v96, 4, v92
	v_add_u32_e32 v92, s0, v96
	v_ashrrev_i32_e32 v93, 31, v92
	v_lshlrev_b64 v[92:93], 13, v[92:93]
	v_lshl_add_u64 v[92:93], v[6:7], 0, v[92:93]
	global_load_dwordx4 v[92:95], v[92:93], off
	v_mad_u64_u32 v[6:7], s[14:15], v96, s18, v[0:1]
	s_waitcnt vmcnt(1)
	ds_write2_b32 v8, v2, v3 offset1:1
	ds_write2_b32 v8, v4, v5 offset0:2 offset1:3
	v_ashrrev_i32_e32 v0, 3, v10
	s_waitcnt vmcnt(0)
	ds_write2_b32 v6, v92, v93 offset1:1
	ds_write2_b32 v6, v94, v95 offset0:2 offset1:3
	v_lshlrev_b32_e32 v2, 3, v10
	v_and_b32_e32 v10, 56, v2
	v_lshlrev_b32_e32 v2, 2, v0
	v_mul_u32_u24_e32 v3, 0x104, v10
	v_add3_u32 v6, 0, v2, v3
	s_waitcnt lgkmcnt(0)
	s_barrier
	ds_read2_b32 v[2:3], v6 offset1:65
	ds_read2_b32 v[4:5], v6 offset0:130 offset1:195
	v_add_u32_e32 v8, 0x400, v6
	ds_read2_b32 v[6:7], v8 offset0:4 offset1:69
	ds_read2_b32 v[8:9], v8 offset0:134 offset1:199
	v_subrev_u32_e32 v0, s1, v0
	s_waitcnt lgkmcnt(3)
	v_cvt_pk_bf16_f32 v2, v2, v3
	s_waitcnt lgkmcnt(2)
	v_cvt_pk_bf16_f32 v3, v4, v5
	s_waitcnt lgkmcnt(1)
	v_cvt_pk_bf16_f32 v4, v6, v7
	v_add_u32_e32 v6, s6, v0
	v_ashrrev_i32_e32 v7, 31, v6
	v_lshlrev_b64 v[6:7], 12, v[6:7]
	v_lshl_add_u64 v[6:7], s[16:17], 0, v[6:7]
	s_ashr_i32 s1, s0, 31
	v_lshl_add_u64 v[6:7], s[0:1], 1, v[6:7]
	v_lshlrev_b32_e32 v0, 1, v10
	s_add_i32 s6, s6, s7
	s_waitcnt lgkmcnt(0)
	v_cvt_pk_bf16_f32 v5, v8, v9
	v_lshl_add_u64 v[6:7], v[6:7], 0, v[0:1]
	s_cmpk_gt_i32 s12, 0x3ff
	global_store_dwordx4 v[6:7], v[2:5], off
	s_barrier
	s_cbranch_scc0 .LBB0_689

; #define LAS __attribute__((address_space(3)))
; __device__ __forceinline__ unsigned cvt_pk_bf16(float lo, float hi) { const f32x2 v = {lo, hi}; const bf16v2 r = __builtin_convertvector(v, bf16v2); return __builtin_bit_cast(unsigned, r); }
; __device__ __forceinline__ void convert_tile(LAS float* tile, const float* __restrict__ src, int N, int k0, int n0, bf16_t* __restrict__ dst, int K, int dst_row0) {
;     ...
;     for (int i = 0; i < 2; ++i) { const int idx = tid + 512 * i, k = idx >> 4, n4 = (idx & 15) * 4;
;         const f32x4 v = *(const f32x4*)(src + (size_t)(k0 + k) * N + n0 + n4);
;         tile[k * 65 + n4] = v[0]; tile[k * 65 + n4 + 1] = v[1]; tile[k * 65 + n4 + 2] = v[2]; tile[k * 65 + n4 + 3] = v[3]; }
;     __syncthreads();
;     { const int n = tid >> 3, kc = (tid & 7) * 8; float f[8];
; #pragma unroll
;       for (int j = 0; j < 8; ++j) f[j] = tile[(kc + j) * 65 + n];
;       u32x4 w; w.x = cvt_pk_bf16(f[0], f[1]); w.y = cvt_pk_bf16(f[2], f[3]); w.z = cvt_pk_bf16(f[4], f[5]); w.w = cvt_pk_bf16(f[6], f[7]);
;       *(u32x4*)(dst + (size_t)(dst_row0 + n) * K + k0 + kc) = w; }
;     __syncthreads();
; }
; __device__ void convert_mat(LAS float* tile, const float* src, int K, int N, bf16_t* dst, int mode, int rank, int stride) {
;     const int nnt = N / 64, nt = (K / 64) * nnt;
;     for (int t = rank; t < nt; t += stride) { const int kt = t / nnt, n0 = (t % nnt) * 64;
;         const int drow = mode == 0 ? n0 : (n0 >> 7) * 256 + (n0 & 127) + (mode - 1) * 128;
;         convert_tile(tile, src, N, kt * 64, n0, dst, K, drow); }
.LBB0_694:
	s_ashr_i32 s0, s12, 31
	s_lshr_b32 s0, s0, 27
	s_add_i32 s0, s12, s0
	s_ashr_i32 s0, s0, 5
	s_lshl_b32 s1, s0, 11
	s_sub_i32 s14, s6, s1
	v_mov_b32_e32 v10, v226
	s_ashr_i32 s15, s14, 31
	s_lshl_b32 s0, s0, 6
	s_lshl_b64 s[14:15], s[14:15], 2
	v_ashrrev_i32_e32 v8, 4, v10
	s_add_u32 s14, s4, s14
	v_lshlrev_b32_e32 v0, 4, v10
	v_add_u32_e32 v2, s0, v8
	s_addc_u32 s15, s5, s15
	v_and_b32_e32 v0, 0xf0, v0
	v_ashrrev_i32_e32 v3, 31, v2
	v_lshl_add_u64 v[6:7], s[14:15], 0, v[0:1]
	v_lshlrev_b64 v[2:3], 13, v[2:3]
	v_lshl_add_u64 v[2:3], v[6:7], 0, v[2:3]
	global_load_dwordx4 v[2:5], v[2:3], off
	v_add_u32_e32 v0, 0, v0
	v_mad_u64_u32 v[8:9], s[14:15], v8, s18, v[0:1]
	s_add_i32 s12, s12, s3
	v_add_u32_e32 v92, 0x200, v10
	v_ashrrev_i32_e32 v96, 4, v92
	v_add_u32_e32 v92, s0, v96
	v_ashrrev_i32_e32 v93, 31, v92
	v_lshlrev_b64 v[92:93], 13, v[92:93]
	v_lshl_add_u64 v[92:93], v[6:7], 0, v[92:93]
	global_load_dwordx4 v[92:95], v[92:93], off
	v_mad_u64_u32 v[6:7], s[14:15], v96, s18, v[0:1]
	s_waitcnt vmcnt(1)
	ds_write2_b32 v8, v2, v3 offset1:1
	ds_write2_b32 v8, v4, v5 offset0:2 offset1:3
	v_ashrrev_i32_e32 v0, 3, v10
	s_waitcnt vmcnt(0)
	ds_write2_b32 v6, v92, v93 offset1:1
	ds_write2_b32 v6, v94, v95 offset0:2 offset1:3
	v_lshlrev_b32_e32 v2, 3, v10
	v_and_b32_e32 v10, 56, v2
	v_lshlrev_b32_e32 v2, 2, v0
	v_mul_u32_u24_e32 v3, 0x104, v10
	v_add3_u32 v6, 0, v2, v3
	s_waitcnt lgkmcnt(0)
	s_barrier
	ds_read2_b32 v[2:3], v6 offset1:65
	ds_read2_b32 v[4:5], v6 offset0:130 offset1:195
	v_add_u32_e32 v8, 0x400, v6
	ds_read2_b32 v[6:7], v8 offset0:4 offset1:69
	ds_read2_b32 v[8:9], v8 offset0:134 offset1:199
	v_subrev_u32_e32 v0, s1, v0
	s_waitcnt lgkmcnt(3)
	v_cvt_pk_bf16_f32 v2, v2, v3
	s_waitcnt lgkmcnt(2)
	v_cvt_pk_bf16_f32 v3, v4, v5
	s_waitcnt lgkmcnt(1)
	v_cvt_pk_bf16_f32 v4, v6, v7
	v_add_u32_e32 v0, s6, v0
	v_mov_b64_e32 v[6:7], s[86:87]
	v_mad_i64_i32 v[6:7], s[14:15], v0, s13, v[6:7]
	s_ashr_i32 s1, s0, 31
	v_lshl_add_u64 v[6:7], s[0:1], 1, v[6:7]
	v_lshlrev_b32_e32 v0, 1, v10
	s_add_i32 s6, s6, s7
	s_waitcnt lgkmcnt(0)
	v_cvt_pk_bf16_f32 v5, v8, v9
	v_lshl_add_u64 v[6:7], v[6:7], 0, v[0:1]
	s_cmpk_lt_i32 s12, 0xac0
	global_store_dwordx4 v[6:7], v[2:5], off
	s_barrier
	s_cbranch_scc1 .LBB0_694

; #define LAS __attribute__((address_space(3)))
; __device__ __forceinline__ unsigned cvt_pk_bf16(float lo, float hi) { const f32x2 v = {lo, hi}; const bf16v2 r = __builtin_convertvector(v, bf16v2); return __builtin_bit_cast(unsigned, r); }
; __device__ __forceinline__ void convert_tile(LAS float* tile, const float* __restrict__ src, int N, int k0, int n0, bf16_t* __restrict__ dst, int K, int dst_row0) {
;     ...
;     for (int i = 0; i < 2; ++i) { const int idx = tid + 512 * i, k = idx >> 4, n4 = (idx & 15) * 4;
;         const f32x4 v = *(const f32x4*)(src + (size_t)(k0 + k) * N + n0 + n4);
;         tile[k * 65 + n4] = v[0]; tile[k * 65 + n4 + 1] = v[1]; tile[k * 65 + n4 + 2] = v[2]; tile[k * 65 + n4 + 3] = v[3]; }
;     __syncthreads();
;     { const int n = tid >> 3, kc = (tid & 7) * 8; float f[8];
; #pragma unroll
;       for (int j = 0; j < 8; ++j) f[j] = tile[(kc + j) * 65 + n];
;       u32x4 w; w.x = cvt_pk_bf16(f[0], f[1]); w.y = cvt_pk_bf16(f[2], f[3]); w.z = cvt_pk_bf16(f[4], f[5]); w.w = cvt_pk_bf16(f[6], f[7]);
;       *(u32x4*)(dst + (size_t)(dst_row0 + n) * K + k0 + kc) = w; }
;     __syncthreads();
; }
; __device__ void convert_mat(LAS float* tile, const float* src, int K, int N, bf16_t* dst, int mode, int rank, int stride) {
;     const int nnt = N / 64, nt = (K / 64) * nnt;
;     for (int t = rank; t < nt; t += stride) { const int kt = t / nnt, n0 = (t % nnt) * 64;
;         const int drow = mode == 0 ? n0 : (n0 >> 7) * 256 + (n0 & 127) + (mode - 1) * 128;
;         convert_tile(tile, src, N, kt * 64, n0, dst, K, drow); }
.LBB0_697:
	s_mul_hi_i32 s0, s2, 0x92492493
	s_add_i32 s0, s0, s2
	s_lshr_b32 s1, s0, 31
	s_ashr_i32 s0, s0, 6
	s_add_i32 s1, s0, s1
	s_mul_i32 s0, s1, 0xffffe400
	s_add_i32 s12, s6, s0
	s_ashr_i32 s13, s12, 31
	s_lshl_b32 s0, s1, 6
	v_mov_b32_e32 v10, v226
	s_lshl_b64 s[12:13], s[12:13], 2
	s_add_u32 s12, s4, s12
	v_lshlrev_b32_e32 v0, 4, v10
	s_addc_u32 s13, s5, s13
	v_and_b32_e32 v0, 0xf0, v0
	v_ashrrev_i32_e32 v8, 4, v10
	v_lshl_add_u64 v[6:7], s[12:13], 0, v[0:1]
	v_add_u32_e32 v2, s0, v8
	v_mad_i64_i32 v[2:3], s[12:13], v2, s20, v[6:7]
	global_load_dwordx4 v[2:5], v[2:3], off
	v_add_u32_e32 v0, 0, v0
	v_mad_u64_u32 v[8:9], s[12:13], v8, s18, v[0:1]
	s_mulk_i32 s1, 0x1c00
	s_add_i32 s2, s2, s3
	v_add_u32_e32 v92, 0x200, v10
	v_ashrrev_i32_e32 v96, 4, v92
	v_add_u32_e32 v92, s0, v96
	v_mad_i64_i32 v[92:93], s[12:13], v92, s20, v[6:7]
	global_load_dwordx4 v[92:95], v[92:93], off
	v_mad_u64_u32 v[6:7], s[12:13], v96, s18, v[0:1]
	s_waitcnt vmcnt(1)
	ds_write2_b32 v8, v2, v3 offset1:1
	ds_write2_b32 v8, v4, v5 offset0:2 offset1:3
	v_ashrrev_i32_e32 v0, 3, v10
	s_waitcnt vmcnt(0)
	ds_write2_b32 v6, v92, v93 offset1:1
	ds_write2_b32 v6, v94, v95 offset0:2 offset1:3
	v_lshlrev_b32_e32 v2, 3, v10
	v_and_b32_e32 v10, 56, v2
	v_lshlrev_b32_e32 v2, 2, v0
	v_mul_u32_u24_e32 v3, 0x104, v10
	v_add3_u32 v6, 0, v2, v3
	s_waitcnt lgkmcnt(0)
	s_barrier
	ds_read2_b32 v[2:3], v6 offset1:65
	ds_read2_b32 v[4:5], v6 offset0:130 offset1:195
	v_add_u32_e32 v8, 0x400, v6
	ds_read2_b32 v[6:7], v8 offset0:4 offset1:69
	ds_read2_b32 v[8:9], v8 offset0:134 offset1:199
	v_subrev_u32_e32 v0, s1, v0
	s_waitcnt lgkmcnt(3)
	v_cvt_pk_bf16_f32 v2, v2, v3
	s_waitcnt lgkmcnt(2)
	v_cvt_pk_bf16_f32 v3, v4, v5
	s_waitcnt lgkmcnt(1)
	v_cvt_pk_bf16_f32 v4, v6, v7
	v_add_u32_e32 v6, s6, v0
	v_ashrrev_i32_e32 v7, 31, v6
	v_lshlrev_b64 v[6:7], 12, v[6:7]
	v_lshl_add_u64 v[6:7], s[88:89], 0, v[6:7]
	s_ashr_i32 s1, s0, 31
	v_lshl_add_u64 v[6:7], s[0:1], 1, v[6:7]
	v_lshlrev_b32_e32 v0, 1, v10
	s_add_i32 s6, s6, s7
	s_waitcnt lgkmcnt(0)
	v_cvt_pk_bf16_f32 v5, v8, v9
	v_lshl_add_u64 v[6:7], v[6:7], 0, v[0:1]
	s_cmpk_gt_i32 s2, 0xdff
	global_store_dwordx4 v[6:7], v[2:5], off
	s_barrier
	s_cbranch_scc0 .LBB0_697
